# RES context split-K partial slabs stored write-through (sc1 dwordx4) so the grid barrier's L2 writeback finds them clean
# speedup vs baseline: 1.0090x; 1.0006x over previous
.Lres_isc_fast:
	v_readlane_b32 s6, v253, 29
	v_mov_b32_e32 v176, s6
	ds_read_b64 v[176:177], v176
	s_ashr_i32 s4, s26, 1
	s_ashr_i32 s5, s4, 31
	s_lshl_b64 s[4:5], s[4:5], 20
	s_waitcnt lgkmcnt(0)
	v_lshl_add_u64 v[176:177], v[176:177], 0, s[4:5]
	v_lshl_add_u64 v[176:177], v[170:171], 2, v[176:177]
	s_mov_b64 s[4:5], 0x10000
	s_mov_b64 s[6:7], 0x50000
	s_waitcnt vmcnt(0)
	v_pk_mul_f32 v[206:207], v[126:127], v[142:143]
	v_pk_mul_f32 v[208:209], v[128:129], v[144:145]
	v_pk_mul_f32 v[210:211], v[118:119], v[138:139]
	v_pk_mul_f32 v[212:213], v[120:121], v[140:141]
	v_pk_mul_f32 v[214:215], v[122:123], v[134:135]
	v_pk_mul_f32 v[216:217], v[124:125], v[136:137]
	v_pk_mul_f32 v[218:219], v[114:115], v[130:131]
	v_pk_mul_f32 v[220:221], v[116:117], v[132:133]
	global_store_dwordx4 v[176:177], v[206:209], off sc1
	global_store_dwordx4 v[176:177], v[210:213], off offset:64 sc1
	global_store_dwordx4 v[176:177], v[214:217], off offset:512 sc1
	global_store_dwordx4 v[176:177], v[218:221], off offset:576 sc1
	s_nop 0
	v_lshl_add_u64 v[176:177], v[176:177], 0, s[4:5]
	v_pk_mul_f32 v[222:223], v[110:111], v[142:143]
	v_pk_mul_f32 v[224:225], v[112:113], v[144:145]
	v_pk_mul_f32 v[226:227], v[102:103], v[138:139]
	v_pk_mul_f32 v[228:229], v[104:105], v[140:141]
	v_pk_mul_f32 v[236:237], v[106:107], v[134:135]
	v_pk_mul_f32 v[238:239], v[108:109], v[136:137]
	v_pk_mul_f32 v[240:241], v[98:99], v[130:131]
	v_pk_mul_f32 v[242:243], v[100:101], v[132:133]
	global_store_dwordx4 v[176:177], v[222:225], off sc1
	global_store_dwordx4 v[176:177], v[226:229], off offset:64 sc1
	global_store_dwordx4 v[176:177], v[236:239], off offset:512 sc1
	global_store_dwordx4 v[176:177], v[240:243], off offset:576 sc1
	s_nop 0
	v_lshl_add_u64 v[176:177], v[176:177], 0, s[4:5]
	v_pk_mul_f32 v[244:245], v[94:95], v[142:143]
	v_pk_mul_f32 v[246:247], v[96:97], v[144:145]
	v_pk_mul_f32 v[146:147], v[86:87], v[138:139]
	v_pk_mul_f32 v[148:149], v[88:89], v[140:141]
	v_pk_mul_f32 v[168:169], v[90:91], v[134:135]
	v_pk_mul_f32 v[170:171], v[92:93], v[136:137]
	v_pk_mul_f32 v[164:165], v[82:83], v[130:131]
	v_pk_mul_f32 v[166:167], v[84:85], v[132:133]
	global_store_dwordx4 v[176:177], v[244:247], off sc1
	global_store_dwordx4 v[176:177], v[146:149], off offset:64 sc1
	global_store_dwordx4 v[176:177], v[168:171], off offset:512 sc1
	global_store_dwordx4 v[176:177], v[164:167], off offset:576 sc1
	s_nop 0
	v_lshl_add_u64 v[176:177], v[176:177], 0, s[4:5]
	v_pk_mul_f32 v[206:207], v[78:79], v[142:143]
	v_pk_mul_f32 v[208:209], v[80:81], v[144:145]
	v_pk_mul_f32 v[210:211], v[70:71], v[138:139]
	v_pk_mul_f32 v[212:213], v[72:73], v[140:141]
	v_pk_mul_f32 v[214:215], v[74:75], v[134:135]
	v_pk_mul_f32 v[216:217], v[76:77], v[136:137]
	v_pk_mul_f32 v[218:219], v[66:67], v[130:131]
	v_pk_mul_f32 v[220:221], v[68:69], v[132:133]
	global_store_dwordx4 v[176:177], v[206:209], off sc1
	global_store_dwordx4 v[176:177], v[210:213], off offset:64 sc1
	global_store_dwordx4 v[176:177], v[214:217], off offset:512 sc1
	global_store_dwordx4 v[176:177], v[218:221], off offset:576 sc1
	s_nop 0
	v_lshl_add_u64 v[176:177], v[176:177], 0, s[6:7]
	v_pk_mul_f32 v[222:223], v[62:63], v[142:143]
	v_pk_mul_f32 v[224:225], v[64:65], v[144:145]
	v_pk_mul_f32 v[226:227], v[54:55], v[138:139]
	v_pk_mul_f32 v[228:229], v[56:57], v[140:141]
	v_pk_mul_f32 v[236:237], v[58:59], v[134:135]
	v_pk_mul_f32 v[238:239], v[60:61], v[136:137]
	v_pk_mul_f32 v[240:241], v[50:51], v[130:131]
	v_pk_mul_f32 v[242:243], v[52:53], v[132:133]
	global_store_dwordx4 v[176:177], v[222:225], off sc1
	global_store_dwordx4 v[176:177], v[226:229], off offset:64 sc1
	global_store_dwordx4 v[176:177], v[236:239], off offset:512 sc1
	global_store_dwordx4 v[176:177], v[240:243], off offset:576 sc1
	s_nop 0
	v_lshl_add_u64 v[176:177], v[176:177], 0, s[4:5]
	v_pk_mul_f32 v[244:245], v[46:47], v[142:143]
	v_pk_mul_f32 v[246:247], v[48:49], v[144:145]
	v_pk_mul_f32 v[146:147], v[38:39], v[138:139]
	v_pk_mul_f32 v[148:149], v[40:41], v[140:141]
	v_pk_mul_f32 v[168:169], v[42:43], v[134:135]
	v_pk_mul_f32 v[170:171], v[44:45], v[136:137]
	v_pk_mul_f32 v[164:165], v[34:35], v[130:131]
	v_pk_mul_f32 v[166:167], v[36:37], v[132:133]
	global_store_dwordx4 v[176:177], v[244:247], off sc1
	global_store_dwordx4 v[176:177], v[146:149], off offset:64 sc1
	global_store_dwordx4 v[176:177], v[168:171], off offset:512 sc1
	global_store_dwordx4 v[176:177], v[164:167], off offset:576 sc1
	s_nop 0
	v_lshl_add_u64 v[176:177], v[176:177], 0, s[4:5]
	v_pk_mul_f32 v[206:207], v[30:31], v[142:143]
	v_pk_mul_f32 v[208:209], v[32:33], v[144:145]
	v_pk_mul_f32 v[210:211], v[22:23], v[138:139]
	v_pk_mul_f32 v[212:213], v[24:25], v[140:141]
	v_pk_mul_f32 v[214:215], v[26:27], v[134:135]
	v_pk_mul_f32 v[216:217], v[28:29], v[136:137]
	v_pk_mul_f32 v[218:219], v[18:19], v[130:131]
	v_pk_mul_f32 v[220:221], v[20:21], v[132:133]
	global_store_dwordx4 v[176:177], v[206:209], off sc1
	global_store_dwordx4 v[176:177], v[210:213], off offset:64 sc1
	global_store_dwordx4 v[176:177], v[214:217], off offset:512 sc1
	global_store_dwordx4 v[176:177], v[218:221], off offset:576 sc1
	s_nop 0
	v_lshl_add_u64 v[176:177], v[176:177], 0, s[4:5]
	v_pk_mul_f32 v[222:223], v[14:15], v[142:143]
	v_pk_mul_f32 v[224:225], v[16:17], v[144:145]
	v_pk_mul_f32 v[226:227], v[6:7], v[138:139]
	v_pk_mul_f32 v[228:229], v[8:9], v[140:141]
	v_pk_mul_f32 v[236:237], v[10:11], v[134:135]
	v_pk_mul_f32 v[238:239], v[12:13], v[136:137]
	v_pk_mul_f32 v[240:241], v[2:3], v[130:131]
	v_pk_mul_f32 v[242:243], v[4:5], v[132:133]
	global_store_dwordx4 v[176:177], v[222:225], off sc1
	global_store_dwordx4 v[176:177], v[226:229], off offset:64 sc1
	global_store_dwordx4 v[176:177], v[236:239], off offset:512 sc1
	global_store_dwordx4 v[176:177], v[240:243], off offset:576 sc1
	s_branch .LBB0_816
